# attention: removed x+0 adds on the (strictly positive) row-sum chain
# speedup vs baseline: 1.0009x; 1.0009x over previous
; __device__ __forceinline__ void glds16(const void*gsrc,unsigned lds_dst){unsigned keep;
;   asm volatile("s_mov_b32 %0, m0\n\ts_mov_b32 m0, %2\n\ts_nop 0\n\tglobal_load_lds_dwordx4 %1, off\n\ts_mov_b32 m0, %0":"=&s"(keep):"v"(gsrc),"s"(lds_dst):"memory");}
.LBB0_778:
	v_add_u32_e32 v214, s22, v209
	ds_read_b64_tr_b16 v[176:177], v214 offset:24576
	ds_read_b64_tr_b16 v[178:179], v214 offset:25088
	s_waitcnt lgkmcnt(9)
	v_mfma_f32_32x32x16_bf16 v[96:111], v[172:175], v[140:143], v[32:47]
	v_add_f32_e32 v80, v64, v65
	v_add_f32_e32 v80, v66, v80
	v_add_f32_e32 v80, v67, v80
	v_add_f32_e32 v80, v68, v80
	v_add_f32_e32 v80, v69, v80
	v_cvt_pk_bf16_f32 v132, v64, v65
	v_cvt_pk_bf16_f32 v133, v66, v67
	ds_read_b64_tr_b16 v[172:173], v214 offset:28672
	ds_read_b64_tr_b16 v[174:175], v214 offset:29184
	v_add_f32_e32 v64, v70, v80
	s_waitcnt lgkmcnt(10)
	v_mfma_f32_32x32x16_bf16 v[80:95], v[168:171], v[140:143], v[32:47]
	v_add_f32_e32 v64, v71, v64
	v_add_f32_e32 v64, v72, v64
	v_add_f32_e32 v112, v73, v64
	v_cvt_pk_bf16_f32 v134, v68, v69
	v_cvt_pk_bf16_f32 v135, v70, v71
	ds_read_b64_tr_b16 v[64:65], v214 offset:25600
	ds_read_b64_tr_b16 v[66:67], v214 offset:26112
	s_waitcnt lgkmcnt(11)
	v_mfma_f32_32x32x16_bf16 v[96:111], v[164:167], v[136:139], v[96:111]
	v_add_f32_e32 v68, v74, v112
	v_add_f32_e32 v68, v75, v68
	v_add_f32_e32 v68, v76, v68
	v_add_f32_e32 v112, v77, v68
	v_cvt_pk_bf16_f32 v124, v72, v73
	v_cvt_pk_bf16_f32 v125, v74, v75
	ds_read_b64_tr_b16 v[68:69], v214 offset:29696
	ds_read_b64_tr_b16 v[70:71], v214 offset:30208
	s_waitcnt lgkmcnt(12)
	v_mfma_f32_32x32x16_bf16 v[80:95], v[160:163], v[136:139], v[80:95]
	v_add_f32_e32 v72, v78, v112
	v_add_f32_e32 v72, v79, v72
	v_add_f32_e32 v72, v48, v72
	v_add_f32_e32 v112, v49, v72
	v_cvt_pk_bf16_f32 v126, v76, v77
	v_cvt_pk_bf16_f32 v127, v78, v79
	ds_read_b64_tr_b16 v[72:73], v214 offset:26624
	ds_read_b64_tr_b16 v[74:75], v214 offset:27136
	s_waitcnt lgkmcnt(13)
	v_mfma_f32_32x32x16_bf16 v[96:111], v[156:159], v[128:131], v[96:111]
	v_add_f32_e32 v76, v50, v112
	v_add_f32_e32 v76, v51, v76
	v_add_f32_e32 v76, v52, v76
	v_add_f32_e32 v76, v53, v76
	v_cvt_pk_bf16_f32 v116, v48, v49
	v_cvt_pk_bf16_f32 v117, v50, v51
	ds_read_b64_tr_b16 v[48:49], v214 offset:30720
	ds_read_b64_tr_b16 v[50:51], v214 offset:31232
	s_waitcnt lgkmcnt(14)
	v_mfma_f32_32x32x16_bf16 v[80:95], v[152:155], v[128:131], v[80:95]
	v_add_f32_e32 v76, v54, v76
	v_add_f32_e32 v76, v55, v76
	v_add_f32_e32 v76, v56, v76
	v_add_f32_e32 v76, v57, v76
	v_cvt_pk_bf16_f32 v118, v52, v53
	v_cvt_pk_bf16_f32 v119, v54, v55
	ds_read_b64_tr_b16 v[52:53], v214 offset:27648
	ds_read_b64_tr_b16 v[54:55], v214 offset:28160
	s_waitcnt lgkmcnt(14)
	v_mfma_f32_32x32x16_bf16 v[96:111], v[148:151], v[120:123], v[96:111]
	v_add_f32_e32 v76, v58, v76
	v_add_f32_e32 v76, v59, v76
	v_add_f32_e32 v76, v60, v76
	v_add_f32_e32 v76, v61, v76
	v_cvt_pk_bf16_f32 v112, v56, v57
	v_cvt_pk_bf16_f32 v113, v58, v59
	ds_read_b64_tr_b16 v[56:57], v214 offset:31744
	ds_read_b64_tr_b16 v[58:59], v214 offset:32256
	v_mfma_f32_32x32x16_bf16 v[80:95], v[144:147], v[120:123], v[80:95]
	v_add_f32_e32 v76, v62, v76
	v_add_f32_e32 v76, v63, v76
	v_cvt_pk_bf16_f32 v114, v60, v61
	v_cvt_pk_bf16_f32 v115, v62, v63
	v_lshl_add_u64 v[60:61], v[192:193], 0, s[86:87]
	s_add_i32 s22, s3, s38
	s_mov_b32 s23, m0
	s_mov_b32 m0, s22
	s_nop 0
	global_load_lds_dwordx4 v[60:61], off
	s_mov_b32 m0, s23
	v_lshl_add_u64 v[60:61], v[194:195], 0, s[82:83]
	s_add_i32 s22, s53, s39
	s_mov_b32 s23, m0
	s_mov_b32 m0, s22
	s_nop 0
	global_load_lds_dwordx4 v[60:61], off
	s_mov_b32 m0, s23
	v_max_f32_e32 v60, v96, v97
	v_max3_f32 v61, v98, v99, v81
	v_max3_f32 v60, v60, v80, v82
	v_max3_f32 v60, v60, v83, v100
	v_max3_f32 v61, v61, v102, v103
	v_max3_f32 v60, v60, v101, v84
	v_max3_f32 v61, v61, v86, v87
	v_max3_f32 v60, v60, v85, v104
	v_max3_f32 v61, v61, v106, v107
	v_max3_f32 v60, v60, v105, v88
	v_max3_f32 v61, v61, v90, v91
	v_max3_f32 v60, v60, v89, v108
	v_max3_f32 v61, v61, v110, v111
	v_max3_f32 v60, v60, v109, v92
	v_max3_f32 v61, v61, v94, v95
	v_max3_f32 v60, v60, v93, v61
	v_mov_b32_e32 v61, v60
	s_nop 1
	v_permlane32_swap_b32_e32 v60, v61
	v_max_f32_e32 v60, v60, v61
	v_cmp_lt_f32_e32 vcc, s12, v60
	s_cmp_lg_u64 vcc, 0
	v_add_f32_e32 v180, v180, v76
	s_cselect_b64 s[42:43], -1, 0
	s_cbranch_vccnz .LBB0_786

.LBB0_781:
	s_add_i32 s22, s53, 0x2000
	s_cmpk_lg_i32 s53, 0x4000
	s_cselect_b32 s44, s22, 0
	v_add_u32_e32 v214, s3, v209
	ds_read_b64_tr_b16 v[148:149], v214 offset:24576
	ds_read_b64_tr_b16 v[150:151], v214 offset:25088
	s_waitcnt lgkmcnt(9)
	v_mfma_f32_32x32x16_bf16 v[64:79], v[60:63], v[140:143], v[32:47]
	v_add_f32_e32 v48, v96, v97
	v_add_f32_e32 v48, v98, v48
	v_add_f32_e32 v48, v99, v48
	v_add_f32_e32 v48, v100, v48
	v_add_f32_e32 v48, v101, v48
	v_cvt_pk_bf16_f32 v132, v96, v97
	v_cvt_pk_bf16_f32 v133, v98, v99
	ds_read_b64_tr_b16 v[144:145], v214 offset:28672
	ds_read_b64_tr_b16 v[146:147], v214 offset:29184
	v_add_f32_e32 v48, v102, v48
	v_add_f32_e32 v48, v103, v48
	v_add_f32_e32 v48, v104, v48
	v_add_f32_e32 v112, v105, v48
	s_waitcnt lgkmcnt(10)
	v_mfma_f32_32x32x16_bf16 v[48:63], v[172:175], v[140:143], v[32:47]
	v_cvt_pk_bf16_f32 v134, v100, v101
	v_cvt_pk_bf16_f32 v135, v102, v103
	ds_read_b64_tr_b16 v[96:97], v214 offset:25600
	ds_read_b64_tr_b16 v[98:99], v214 offset:26112
	s_waitcnt lgkmcnt(11)
	v_mfma_f32_32x32x16_bf16 v[64:79], v[176:179], v[136:139], v[64:79]
	v_add_f32_e32 v100, v106, v112
	v_add_f32_e32 v100, v107, v100
	v_add_f32_e32 v100, v108, v100
	v_add_f32_e32 v112, v109, v100
	v_cvt_pk_bf16_f32 v124, v104, v105
	v_cvt_pk_bf16_f32 v125, v106, v107
	ds_read_b64_tr_b16 v[100:101], v214 offset:29696
	ds_read_b64_tr_b16 v[102:103], v214 offset:30208
	s_waitcnt lgkmcnt(12)
	v_mfma_f32_32x32x16_bf16 v[48:63], v[168:171], v[136:139], v[48:63]
	v_add_f32_e32 v104, v110, v112
	v_add_f32_e32 v104, v111, v104
	v_add_f32_e32 v104, v80, v104
	v_add_f32_e32 v112, v81, v104
	v_cvt_pk_bf16_f32 v126, v108, v109
	v_cvt_pk_bf16_f32 v127, v110, v111
	ds_read_b64_tr_b16 v[104:105], v214 offset:26624
	ds_read_b64_tr_b16 v[106:107], v214 offset:27136
	s_waitcnt lgkmcnt(13)
	v_mfma_f32_32x32x16_bf16 v[64:79], v[164:167], v[128:131], v[64:79]
	v_add_f32_e32 v108, v82, v112
	v_add_f32_e32 v108, v83, v108
	v_add_f32_e32 v108, v84, v108
	v_add_f32_e32 v108, v85, v108
	v_cvt_pk_bf16_f32 v116, v80, v81
	v_cvt_pk_bf16_f32 v117, v82, v83
	ds_read_b64_tr_b16 v[80:81], v214 offset:30720
	ds_read_b64_tr_b16 v[82:83], v214 offset:31232
	s_waitcnt lgkmcnt(14)
	v_mfma_f32_32x32x16_bf16 v[48:63], v[160:163], v[128:131], v[48:63]
	v_add_f32_e32 v108, v86, v108
	v_add_f32_e32 v108, v87, v108
	v_add_f32_e32 v108, v88, v108
	v_add_f32_e32 v108, v89, v108
	v_cvt_pk_bf16_f32 v118, v84, v85
	v_cvt_pk_bf16_f32 v119, v86, v87
	ds_read_b64_tr_b16 v[84:85], v214 offset:27648
	ds_read_b64_tr_b16 v[86:87], v214 offset:28160
	s_waitcnt lgkmcnt(14)
	v_mfma_f32_32x32x16_bf16 v[64:79], v[156:159], v[120:123], v[64:79]
	v_add_f32_e32 v108, v90, v108
	v_add_f32_e32 v108, v91, v108
	v_add_f32_e32 v108, v92, v108
	v_add_f32_e32 v108, v93, v108
	v_cvt_pk_bf16_f32 v112, v88, v89
	v_cvt_pk_bf16_f32 v113, v90, v91
	ds_read_b64_tr_b16 v[88:89], v214 offset:31744
	ds_read_b64_tr_b16 v[90:91], v214 offset:32256
	v_mfma_f32_32x32x16_bf16 v[48:63], v[152:155], v[120:123], v[48:63]
	v_add_f32_e32 v108, v94, v108
	v_add_f32_e32 v108, v95, v108
	v_cvt_pk_bf16_f32 v114, v92, v93
	v_cvt_pk_bf16_f32 v115, v94, v95
	v_lshl_add_u64 v[92:93], v[192:193], 0, s[88:89]
	s_add_i32 s3, s53, s38
	s_mov_b32 s22, m0
	s_mov_b32 m0, s3
	s_nop 0
	global_load_lds_dwordx4 v[92:93], off
	s_mov_b32 m0, s22
	v_max_f32_e32 v92, v64, v65
	s_nop 1
	v_max3_f32 v93, v66, v67, v49
	v_max3_f32 v92, v92, v48, v50
	v_max3_f32 v92, v92, v51, v68
	v_max3_f32 v93, v93, v70, v71
	v_max3_f32 v92, v92, v69, v52
	v_max3_f32 v93, v93, v54, v55
	v_max3_f32 v92, v92, v53, v72
	v_max3_f32 v93, v93, v74, v75
	v_max3_f32 v92, v92, v73, v56
	v_max3_f32 v93, v93, v58, v59
	v_max3_f32 v92, v92, v57, v76
	v_max3_f32 v93, v93, v78, v79
	v_max3_f32 v92, v92, v77, v60
	v_max3_f32 v93, v93, v62, v63
	v_max3_f32 v92, v92, v61, v93
	v_mov_b32_e32 v93, v92
	s_nop 1
	v_permlane32_swap_b32_e32 v92, v93
	v_max_f32_e32 v92, v92, v93
	v_lshl_add_u64 v[194:195], v[194:195], 0, s[84:85]
	s_add_i32 s3, s44, s39
	s_mov_b32 s22, m0
	s_mov_b32 m0, s3
	s_nop 0
	global_load_lds_dwordx4 v[194:195], off
	s_mov_b32 m0, s22
	v_cmp_lt_f32_e32 vcc, s12, v92
	s_cmp_lg_u64 vcc, 0
	v_add_f32_e32 v180, v180, v108
	s_cselect_b64 s[42:43], -1, 0
	s_cbranch_vccnz .LBB0_789

.LBB0_793:
	v_add_u32_e32 v192, s22, v209
	ds_read_b64_tr_b16 v[176:177], v192 offset:24576
	ds_read_b64_tr_b16 v[178:179], v192 offset:25088
	s_waitcnt lgkmcnt(9)
	v_mfma_f32_32x32x16_bf16 v[96:111], v[172:175], v[140:143], v[32:47]
	v_add_f32_e32 v80, v64, v65
	v_add_f32_e32 v80, v66, v80
	v_add_f32_e32 v80, v67, v80
	v_add_f32_e32 v80, v68, v80
	v_add_f32_e32 v80, v69, v80
	v_cvt_pk_bf16_f32 v132, v64, v65
	v_cvt_pk_bf16_f32 v133, v66, v67
	ds_read_b64_tr_b16 v[172:173], v192 offset:28672
	ds_read_b64_tr_b16 v[174:175], v192 offset:29184
	v_add_f32_e32 v64, v70, v80
	s_waitcnt lgkmcnt(10)
	v_mfma_f32_32x32x16_bf16 v[80:95], v[168:171], v[140:143], v[32:47]
	v_add_f32_e32 v64, v71, v64
	v_add_f32_e32 v64, v72, v64
	v_add_f32_e32 v112, v73, v64
	v_cvt_pk_bf16_f32 v134, v68, v69
	v_cvt_pk_bf16_f32 v135, v70, v71
	ds_read_b64_tr_b16 v[64:65], v192 offset:25600
	ds_read_b64_tr_b16 v[66:67], v192 offset:26112
	s_waitcnt lgkmcnt(11)
	v_mfma_f32_32x32x16_bf16 v[96:111], v[164:167], v[136:139], v[96:111]
	v_add_f32_e32 v68, v74, v112
	v_add_f32_e32 v68, v75, v68
	v_add_f32_e32 v68, v76, v68
	v_add_f32_e32 v112, v77, v68
	v_cvt_pk_bf16_f32 v124, v72, v73
	v_cvt_pk_bf16_f32 v125, v74, v75
	ds_read_b64_tr_b16 v[68:69], v192 offset:29696
	ds_read_b64_tr_b16 v[70:71], v192 offset:30208
	s_waitcnt lgkmcnt(12)
	v_mfma_f32_32x32x16_bf16 v[80:95], v[160:163], v[136:139], v[80:95]
	v_add_f32_e32 v72, v78, v112
	v_add_f32_e32 v72, v79, v72
	v_add_f32_e32 v72, v48, v72
	v_add_f32_e32 v112, v49, v72
	v_cvt_pk_bf16_f32 v126, v76, v77
	v_cvt_pk_bf16_f32 v127, v78, v79
	ds_read_b64_tr_b16 v[72:73], v192 offset:26624
	ds_read_b64_tr_b16 v[74:75], v192 offset:27136
	s_waitcnt lgkmcnt(13)
	v_mfma_f32_32x32x16_bf16 v[96:111], v[156:159], v[128:131], v[96:111]
	v_add_f32_e32 v76, v50, v112
	v_add_f32_e32 v76, v51, v76
	v_add_f32_e32 v76, v52, v76
	v_add_f32_e32 v76, v53, v76
	v_cvt_pk_bf16_f32 v116, v48, v49
	v_cvt_pk_bf16_f32 v117, v50, v51
	ds_read_b64_tr_b16 v[48:49], v192 offset:30720
	ds_read_b64_tr_b16 v[50:51], v192 offset:31232
	s_waitcnt lgkmcnt(14)
	v_mfma_f32_32x32x16_bf16 v[80:95], v[152:155], v[128:131], v[80:95]
	v_add_f32_e32 v76, v54, v76
	v_add_f32_e32 v76, v55, v76
	v_add_f32_e32 v76, v56, v76
	v_add_f32_e32 v76, v57, v76
	v_cvt_pk_bf16_f32 v118, v52, v53
	v_cvt_pk_bf16_f32 v119, v54, v55
	ds_read_b64_tr_b16 v[52:53], v192 offset:27648
	ds_read_b64_tr_b16 v[54:55], v192 offset:28160
	s_waitcnt lgkmcnt(14)
	v_mfma_f32_32x32x16_bf16 v[96:111], v[148:151], v[120:123], v[96:111]
	v_add_f32_e32 v76, v58, v76
	v_add_f32_e32 v76, v59, v76
	v_add_f32_e32 v76, v60, v76
	v_add_f32_e32 v76, v61, v76
	v_cvt_pk_bf16_f32 v112, v56, v57
	v_cvt_pk_bf16_f32 v113, v58, v59
	ds_read_b64_tr_b16 v[56:57], v192 offset:31744
	ds_read_b64_tr_b16 v[58:59], v192 offset:32256
	v_mfma_f32_32x32x16_bf16 v[80:95], v[144:147], v[120:123], v[80:95]
	v_add_f32_e32 v76, v62, v76
	v_add_f32_e32 v76, v63, v76
	v_cvt_pk_bf16_f32 v114, v60, v61
	v_cvt_pk_bf16_f32 v115, v62, v63
	s_cmp_gt_u32 s3, 60
	s_cselect_b64 s[44:45], -1, 0
	s_and_b64 vcc, exec, s[44:45]
	s_mov_b64 s[50:51], s[42:43]
	s_cbranch_vccnz .LBB0_795
	s_add_i32 s22, s62, s38
	v_lshl_add_u64 v[60:61], v[190:191], 0, s[86:87]
	s_mov_b32 s23, m0
	s_mov_b32 m0, s22
	s_nop 0
	global_load_lds_dwordx4 v[60:61], off
	s_mov_b32 m0, s23
	s_mul_i32 s68, s3, 0x18000
	s_mov_b64 s[50:51], s[68:69]

.LBB0_800:
	v_add_u32_e32 v194, s62, v209
	ds_read_b64_tr_b16 v[148:149], v194 offset:24576
	ds_read_b64_tr_b16 v[150:151], v194 offset:25088
	s_waitcnt lgkmcnt(9)
	v_mfma_f32_32x32x16_bf16 v[64:79], v[60:63], v[140:143], v[32:47]
	v_add_f32_e32 v48, v96, v97
	v_add_f32_e32 v48, v98, v48
	v_add_f32_e32 v48, v99, v48
	v_add_f32_e32 v48, v100, v48
	v_add_f32_e32 v48, v101, v48
	v_cvt_pk_bf16_f32 v132, v96, v97
	v_cvt_pk_bf16_f32 v133, v98, v99
	ds_read_b64_tr_b16 v[144:145], v194 offset:28672
	ds_read_b64_tr_b16 v[146:147], v194 offset:29184
	v_add_f32_e32 v48, v102, v48
	v_add_f32_e32 v48, v103, v48
	v_add_f32_e32 v48, v104, v48
	v_add_f32_e32 v112, v105, v48
	s_waitcnt lgkmcnt(10)
	v_mfma_f32_32x32x16_bf16 v[48:63], v[172:175], v[140:143], v[32:47]
	v_cvt_pk_bf16_f32 v134, v100, v101
	v_cvt_pk_bf16_f32 v135, v102, v103
	ds_read_b64_tr_b16 v[96:97], v194 offset:25600
	ds_read_b64_tr_b16 v[98:99], v194 offset:26112
	s_waitcnt lgkmcnt(11)
	v_mfma_f32_32x32x16_bf16 v[64:79], v[176:179], v[136:139], v[64:79]
	v_add_f32_e32 v100, v106, v112
	v_add_f32_e32 v100, v107, v100
	v_add_f32_e32 v100, v108, v100
	v_add_f32_e32 v112, v109, v100
	v_cvt_pk_bf16_f32 v124, v104, v105
	v_cvt_pk_bf16_f32 v125, v106, v107
	ds_read_b64_tr_b16 v[100:101], v194 offset:29696
	ds_read_b64_tr_b16 v[102:103], v194 offset:30208
	s_waitcnt lgkmcnt(12)
	v_mfma_f32_32x32x16_bf16 v[48:63], v[168:171], v[136:139], v[48:63]
	v_add_f32_e32 v104, v110, v112
	v_add_f32_e32 v104, v111, v104
	v_add_f32_e32 v104, v80, v104
	v_add_f32_e32 v112, v81, v104
	v_cvt_pk_bf16_f32 v126, v108, v109
	v_cvt_pk_bf16_f32 v127, v110, v111
	ds_read_b64_tr_b16 v[104:105], v194 offset:26624
	ds_read_b64_tr_b16 v[106:107], v194 offset:27136
	s_waitcnt lgkmcnt(13)
	v_mfma_f32_32x32x16_bf16 v[64:79], v[164:167], v[128:131], v[64:79]
	v_add_f32_e32 v108, v82, v112
	v_add_f32_e32 v108, v83, v108
	v_add_f32_e32 v108, v84, v108
	v_add_f32_e32 v108, v85, v108
	v_cvt_pk_bf16_f32 v116, v80, v81
	v_cvt_pk_bf16_f32 v117, v82, v83
	ds_read_b64_tr_b16 v[80:81], v194 offset:30720
	ds_read_b64_tr_b16 v[82:83], v194 offset:31232
	s_waitcnt lgkmcnt(14)
	v_mfma_f32_32x32x16_bf16 v[48:63], v[160:163], v[128:131], v[48:63]
	v_add_f32_e32 v108, v86, v108
	v_add_f32_e32 v108, v87, v108
	v_add_f32_e32 v108, v88, v108
	v_add_f32_e32 v108, v89, v108
	v_cvt_pk_bf16_f32 v118, v84, v85
	v_cvt_pk_bf16_f32 v119, v86, v87
	ds_read_b64_tr_b16 v[84:85], v194 offset:27648
	ds_read_b64_tr_b16 v[86:87], v194 offset:28160
	s_waitcnt lgkmcnt(14)
	v_mfma_f32_32x32x16_bf16 v[64:79], v[156:159], v[120:123], v[64:79]
	v_add_f32_e32 v108, v90, v108
	v_add_f32_e32 v108, v91, v108
	v_add_f32_e32 v108, v92, v108
	v_add_f32_e32 v108, v93, v108
	v_cvt_pk_bf16_f32 v112, v88, v89
	v_cvt_pk_bf16_f32 v113, v90, v91
	ds_read_b64_tr_b16 v[88:89], v194 offset:31744
	ds_read_b64_tr_b16 v[90:91], v194 offset:32256
	v_mfma_f32_32x32x16_bf16 v[48:63], v[152:155], v[120:123], v[48:63]
	v_add_f32_e32 v108, v94, v108
	v_add_f32_e32 v108, v95, v108
	v_cvt_pk_bf16_f32 v114, v92, v93
	v_cvt_pk_bf16_f32 v115, v94, v95
	s_cmp_gt_u32 s3, 59
	s_cselect_b64 s[52:53], -1, 0
	s_and_b64 vcc, exec, s[52:53]
	s_cbranch_vccnz .LBB0_802
	v_lshl_add_u64 v[92:93], s[50:51], 1, v[186:187]
	s_add_i32 s22, s73, s38
	v_lshl_add_u64 v[92:93], v[92:93], 0, s[88:89]
	s_mov_b32 s23, m0
	s_mov_b32 m0, s22
	s_nop 0
	global_load_lds_dwordx4 v[92:93], off
	s_mov_b32 m0, s23

;   #define RESC() do{ if(resc){ asm volatile("s_waitcnt lgkmcnt(0)":::"memory"); \
;       _Pragma("unroll") for(int d_=0;d_<2;++d_) _Pragma("unroll") for(int r=0;r<16;++r)o[d_][r]*=wsf[crow(r,hi)]; } }while(0)
; template<int THRL> __device__ __forceinline__ void attn_unit(int b,int h,int qb,const bf16*Q,const bf16*__restrict__ K,const bf16*__restrict__ V,bf16*O,char*shm){
;     ...
;   STEP(pB0,pB1,pA0,pA1,NT-1,false,false,false); RESC();
.LBB0_819:
	ds_read_b64_tr_b16 v[96:97], v209 offset:40960
	ds_read_b64_tr_b16 v[98:99], v209 offset:41472
	v_add_f32_e32 v80, v64, v65
	v_add_f32_e32 v80, v66, v80
	v_add_f32_e32 v80, v67, v80
	v_add_f32_e32 v80, v68, v80
	v_add_f32_e32 v100, v69, v80
	s_waitcnt lgkmcnt(9)
	v_mfma_f32_32x32x16_bf16 v[80:95], v[172:175], v[140:143], v[32:47]
	v_cvt_pk_bf16_f32 v132, v64, v65
	v_cvt_pk_bf16_f32 v133, v66, v67
	ds_read_b64_tr_b16 v[64:65], v209 offset:45056
	ds_read_b64_tr_b16 v[66:67], v209 offset:45568
	s_waitcnt lgkmcnt(10)
	v_mfma_f32_32x32x16_bf16 v[32:47], v[168:171], v[140:143], v[32:47]
	v_add_f32_e32 v100, v70, v100
	v_add_f32_e32 v100, v71, v100
	v_add_f32_e32 v100, v72, v100
	v_add_f32_e32 v100, v73, v100
	v_cvt_pk_bf16_f32 v134, v68, v69
	v_cvt_pk_bf16_f32 v135, v70, v71
	ds_read_b64_tr_b16 v[68:69], v209 offset:41984
	ds_read_b64_tr_b16 v[70:71], v209 offset:42496
	s_waitcnt lgkmcnt(11)
	v_mfma_f32_32x32x16_bf16 v[80:95], v[164:167], v[136:139], v[80:95]
	v_add_f32_e32 v100, v74, v100
	v_add_f32_e32 v100, v75, v100
	v_add_f32_e32 v100, v76, v100
	v_add_f32_e32 v100, v77, v100
	v_cvt_pk_bf16_f32 v124, v72, v73
	v_cvt_pk_bf16_f32 v125, v74, v75
	ds_read_b64_tr_b16 v[72:73], v209 offset:46080
	ds_read_b64_tr_b16 v[74:75], v209 offset:46592
	s_waitcnt lgkmcnt(12)
	v_mfma_f32_32x32x16_bf16 v[32:47], v[160:163], v[136:139], v[32:47]
	v_add_f32_e32 v100, v78, v100
	v_add_f32_e32 v100, v79, v100
	v_add_f32_e32 v100, v48, v100
	v_add_f32_e32 v100, v49, v100
	v_cvt_pk_bf16_f32 v126, v76, v77
	v_cvt_pk_bf16_f32 v127, v78, v79
	ds_read_b64_tr_b16 v[76:77], v209 offset:43008
	ds_read_b64_tr_b16 v[78:79], v209 offset:43520
	s_waitcnt lgkmcnt(13)
	v_mfma_f32_32x32x16_bf16 v[80:95], v[156:159], v[128:131], v[80:95]
	v_add_f32_e32 v100, v50, v100
	v_add_f32_e32 v100, v51, v100
	v_add_f32_e32 v100, v52, v100
	v_add_f32_e32 v104, v53, v100
	v_cvt_pk_bf16_f32 v116, v48, v49
	v_cvt_pk_bf16_f32 v117, v50, v51
	ds_read_b64_tr_b16 v[100:101], v209 offset:47104
	ds_read_b64_tr_b16 v[102:103], v209 offset:47616
	s_waitcnt lgkmcnt(14)
	v_mfma_f32_32x32x16_bf16 v[32:47], v[152:155], v[128:131], v[32:47]
	v_add_f32_e32 v48, v54, v104
	v_add_f32_e32 v48, v55, v48
	v_add_f32_e32 v48, v56, v48
	v_add_f32_e32 v48, v57, v48
	v_cvt_pk_bf16_f32 v118, v52, v53
	v_cvt_pk_bf16_f32 v119, v54, v55
	ds_read_b64_tr_b16 v[104:105], v209 offset:44032
	ds_read_b64_tr_b16 v[106:107], v209 offset:44544
	s_waitcnt lgkmcnt(14)
	v_mfma_f32_32x32x16_bf16 v[80:95], v[148:151], v[120:123], v[80:95]
	v_add_f32_e32 v48, v58, v48
	v_add_f32_e32 v48, v59, v48
	v_add_f32_e32 v48, v60, v48
	v_add_f32_e32 v48, v61, v48
	v_cvt_pk_bf16_f32 v112, v56, v57
	v_cvt_pk_bf16_f32 v113, v58, v59
	ds_read_b64_tr_b16 v[108:109], v209 offset:48128
	ds_read_b64_tr_b16 v[110:111], v209 offset:48640
	v_mfma_f32_32x32x16_bf16 v[32:47], v[144:147], v[120:123], v[32:47]
	v_add_f32_e32 v48, v62, v48
	v_add_f32_e32 v48, v63, v48
	v_cvt_pk_bf16_f32 v114, v60, v61
	v_cvt_pk_bf16_f32 v115, v62, v63
	v_max_f32_e32 v49, v80, v81
	s_nop 3
	v_max3_f32 v50, v82, v83, v33
	v_max3_f32 v49, v49, v32, v34
	v_max3_f32 v49, v49, v35, v84
	v_max3_f32 v50, v50, v86, v87
	v_max3_f32 v49, v49, v85, v36
	v_max3_f32 v50, v50, v38, v39
	v_max3_f32 v49, v49, v37, v88
	v_max3_f32 v50, v50, v90, v91
	v_max3_f32 v49, v49, v89, v40
	v_max3_f32 v50, v50, v42, v43
	v_max3_f32 v49, v49, v41, v92
	v_max3_f32 v50, v50, v94, v95
	v_max3_f32 v49, v49, v93, v44
	v_max3_f32 v50, v50, v46, v47
	v_add_f32_e32 v120, v180, v48
	v_max3_f32 v48, v49, v45, v50
	v_mov_b32_e32 v49, v48
	s_nop 1
	v_permlane32_swap_b32_e32 v48, v49
	v_max_f32_e32 v48, v48, v49
	v_cmp_lt_f32_e32 vcc, s12, v48
	s_cmp_lg_u64 vcc, 0
	s_cselect_b64 s[42:43], -1, 0
	s_cbranch_vccnz .LBB0_824
